# norm phase: hand-written context-row path (split-K slab fold, residual update and norm with all loads in flight)
# speedup vs baseline: 1.0079x; 1.0079x over previous
.Lnf_skip:
	s_andn2_b64 vcc, exec, s[6:7]
	s_cbranch_vccnz .Lnc_skip
	s_add_i32 vcc_lo, s24, 0xffffc000
	s_cmp_lt_u32 s48, vcc_lo
	s_cbranch_scc1 .Lnc_skip
	v_and_b32_e32 v114, 63, v224
	v_mov_b32_e32 v115, 0
	v_mov_b32_e32 v117, 0
	v_lshlrev_b32_e32 v116, 4, v114
	v_lshlrev_b32_e32 v114, 3, v114
	s_cmp_eq_u32 s16, 11
	s_cbranch_scc1 .Lnc_11
	s_cmp_eq_u32 s16, 4
	s_cbranch_scc1 .Lnc_4
	s_cmp_eq_u32 s16, 0
	s_cbranch_scc0 .Lnc_skip
	s_mov_b64 vcc, 0x24000
	v_lshl_add_u64 v[118:119], v[62:63], 0, v[116:117]
	v_lshl_add_u64 v[120:121], v[60:61], 0, v[116:117]
	v_lshl_add_u64 v[118:119], v[118:119], 0, vcc
	v_lshl_add_u64 v[120:121], v[120:121], 0, vcc
	v_lshl_add_u64 v[218:219], v[52:53], 0, v[116:117]
	global_load_dwordx4 v[66:69], v[218:219], off
	global_load_dwordx4 v[70:73], v[218:219], off offset:16
	global_load_dwordx4 v[74:77], v[218:219], off offset:2048
	global_load_dwordx4 v[78:81], v[218:219], off offset:2064
	global_load_dwordx4 v[82:85], v[118:119], off
	global_load_dwordx4 v[86:89], v[118:119], off offset:16
	global_load_dwordx4 v[90:93], v[118:119], off offset:2048
	global_load_dwordx4 v[94:97], v[118:119], off offset:2064
	global_load_dwordx4 v[98:101], v[120:121], off
	global_load_dwordx4 v[102:105], v[120:121], off offset:16
	global_load_dwordx4 v[106:109], v[120:121], off offset:2048
	global_load_dwordx4 v[110:113], v[120:121], off offset:2064
	s_mov_b32 vcc_lo, s25
	s_mov_b32 vcc_hi, 0
	s_lshl_b64 vcc, vcc, 11
	v_lshl_add_u64 v[118:119], v[54:55], 0, v[114:115]
	v_lshl_add_u64 v[118:119], v[118:119], 0, vcc
	global_load_dwordx4 v[122:125], v[118:119], off
	global_load_dwordx4 v[126:129], v[118:119], off offset:1024
	v_mov_b32_e32 v220, 0x3a800000
	v_mov_b32_e32 v221, 0x358637bd
	s_waitcnt vmcnt(2)
	v_pk_add_f32 v[82:83], v[82:83], 1.0 op_sel_hi:[1,0]
	v_pk_add_f32 v[84:85], v[84:85], 1.0 op_sel_hi:[1,0]
	v_pk_add_f32 v[86:87], v[86:87], 1.0 op_sel_hi:[1,0]
	v_pk_add_f32 v[88:89], v[88:89], 1.0 op_sel_hi:[1,0]
	v_pk_add_f32 v[90:91], v[90:91], 1.0 op_sel_hi:[1,0]
	v_pk_add_f32 v[92:93], v[92:93], 1.0 op_sel_hi:[1,0]
	v_pk_add_f32 v[94:95], v[94:95], 1.0 op_sel_hi:[1,0]
	v_pk_add_f32 v[96:97], v[96:97], 1.0 op_sel_hi:[1,0]
	v_pk_mul_f32 v[66:67], v[66:67], v[82:83]
	v_pk_mul_f32 v[68:69], v[68:69], v[84:85]
	v_pk_mul_f32 v[70:71], v[70:71], v[86:87]
	v_pk_mul_f32 v[72:73], v[72:73], v[88:89]
	v_pk_mul_f32 v[74:75], v[74:75], v[90:91]
	v_pk_mul_f32 v[76:77], v[76:77], v[92:93]
	v_pk_mul_f32 v[78:79], v[78:79], v[94:95]
	v_pk_mul_f32 v[80:81], v[80:81], v[96:97]
	s_waitcnt vmcnt(0)
	v_lshlrev_b32_e32 v82, 16, v122
	v_and_b32_e32 v83, 0xffff0000, v122
	v_lshlrev_b32_e32 v84, 16, v123
	v_and_b32_e32 v85, 0xffff0000, v123
	v_lshlrev_b32_e32 v86, 16, v124
	v_and_b32_e32 v87, 0xffff0000, v124
	v_lshlrev_b32_e32 v88, 16, v125
	v_and_b32_e32 v89, 0xffff0000, v125
	v_lshlrev_b32_e32 v90, 16, v126
	v_and_b32_e32 v91, 0xffff0000, v126
	v_lshlrev_b32_e32 v92, 16, v127
	v_and_b32_e32 v93, 0xffff0000, v127
	v_lshlrev_b32_e32 v94, 16, v128
	v_and_b32_e32 v95, 0xffff0000, v128
	v_lshlrev_b32_e32 v96, 16, v129
	v_and_b32_e32 v97, 0xffff0000, v129
	v_mul_f32_e32 v218, v82, v82
	v_mul_f32_e32 v219, v83, v83
	v_fmac_f32_e32 v218, v84, v84
	v_fmac_f32_e32 v219, v85, v85
	v_fmac_f32_e32 v218, v86, v86
	v_fmac_f32_e32 v219, v87, v87
	v_fmac_f32_e32 v218, v88, v88
	v_fmac_f32_e32 v219, v89, v89
	v_fmac_f32_e32 v218, v90, v90
	v_fmac_f32_e32 v219, v91, v91
	v_fmac_f32_e32 v218, v92, v92
	v_fmac_f32_e32 v219, v93, v93
	v_fmac_f32_e32 v218, v94, v94
	v_fmac_f32_e32 v219, v95, v95
	v_fmac_f32_e32 v218, v96, v96
	v_fmac_f32_e32 v219, v97, v97
	v_add_f32_e32 v218, v218, v219
	s_nop 1
	v_add_f32_dpp v218, v218, v218 quad_perm:[1,0,3,2] row_mask:0xf bank_mask:0xf
	s_nop 1
	v_add_f32_dpp v218, v218, v218 quad_perm:[2,3,0,1] row_mask:0xf bank_mask:0xf
	s_nop 1
	v_add_f32_dpp v218, v218, v218 row_half_mirror row_mask:0xf bank_mask:0xf
	s_nop 1
	v_add_f32_dpp v218, v218, v218 row_mirror row_mask:0xf bank_mask:0xf
	s_nop 1
	v_add_f32_dpp v218, v218, v218 row_bcast:15 row_mask:0xa bank_mask:0xf
	s_nop 1
	v_add_f32_dpp v218, v218, v218 row_bcast:31 row_mask:0xc bank_mask:0xf
	s_nop 1
	v_readlane_b32 vcc_lo, v218, 63
	s_nop 2
	v_fma_f32 v222, vcc_lo, v220, v221
	v_rsq_f32_e32 v222, v222
	s_mov_b64 vcc, 0x4400000
	v_lshl_add_u64 v[118:119], v[118:119], 0, vcc
	v_pk_mul_f32 v[82:83], v[82:83], v[222:223] op_sel_hi:[1,0]
	v_pk_fma_f32 v[82:83], v[82:83], v[66:67], v[98:99]
	v_pk_mul_f32 v[84:85], v[84:85], v[222:223] op_sel_hi:[1,0]
	v_pk_fma_f32 v[84:85], v[84:85], v[68:69], v[100:101]
	v_pk_mul_f32 v[86:87], v[86:87], v[222:223] op_sel_hi:[1,0]
	v_pk_fma_f32 v[86:87], v[86:87], v[70:71], v[102:103]
	v_pk_mul_f32 v[88:89], v[88:89], v[222:223] op_sel_hi:[1,0]
	v_pk_fma_f32 v[88:89], v[88:89], v[72:73], v[104:105]
	v_pk_mul_f32 v[90:91], v[90:91], v[222:223] op_sel_hi:[1,0]
	v_pk_fma_f32 v[90:91], v[90:91], v[74:75], v[106:107]
	v_pk_mul_f32 v[92:93], v[92:93], v[222:223] op_sel_hi:[1,0]
	v_pk_fma_f32 v[92:93], v[92:93], v[76:77], v[108:109]
	v_pk_mul_f32 v[94:95], v[94:95], v[222:223] op_sel_hi:[1,0]
	v_pk_fma_f32 v[94:95], v[94:95], v[78:79], v[110:111]
	v_pk_mul_f32 v[96:97], v[96:97], v[222:223] op_sel_hi:[1,0]
	v_pk_fma_f32 v[96:97], v[96:97], v[80:81], v[112:113]
	v_cvt_pk_bf16_f32 v66, v82, v83
	v_cvt_pk_bf16_f32 v67, v84, v85
	v_cvt_pk_bf16_f32 v68, v86, v87
	v_cvt_pk_bf16_f32 v69, v88, v89
	v_cvt_pk_bf16_f32 v70, v90, v91
	v_cvt_pk_bf16_f32 v71, v92, v93
	v_cvt_pk_bf16_f32 v72, v94, v95
	v_cvt_pk_bf16_f32 v73, v96, v97
	global_store_dwordx4 v[118:119], v[66:69], off
	global_store_dwordx4 v[118:119], v[70:73], off offset:1024
	s_branch .Lnc_done
.Lnc_4:
	s_mov_b64 vcc, 0x24000
	v_lshl_add_u64 v[118:119], v[62:63], 0, v[116:117]
	v_lshl_add_u64 v[120:121], v[60:61], 0, v[116:117]
	v_lshl_add_u64 v[118:119], v[118:119], 0, vcc
	v_lshl_add_u64 v[120:121], v[120:121], 0, vcc
	v_lshl_add_u64 v[218:219], v[52:53], 0, v[116:117]
	global_load_dwordx4 v[66:69], v[218:219], off
	global_load_dwordx4 v[70:73], v[218:219], off offset:16
	global_load_dwordx4 v[74:77], v[218:219], off offset:2048
	global_load_dwordx4 v[78:81], v[218:219], off offset:2064
	global_load_dwordx4 v[82:85], v[118:119], off
	global_load_dwordx4 v[86:89], v[118:119], off offset:16
	global_load_dwordx4 v[90:93], v[118:119], off offset:2048
	global_load_dwordx4 v[94:97], v[118:119], off offset:2064
	global_load_dwordx4 v[98:101], v[120:121], off
	global_load_dwordx4 v[102:105], v[120:121], off offset:16
	global_load_dwordx4 v[106:109], v[120:121], off offset:2048
	global_load_dwordx4 v[110:113], v[120:121], off offset:2064
	s_mov_b32 vcc_lo, s25
	s_mov_b32 vcc_hi, 0
	s_lshl_b64 vcc, vcc, 11
	v_lshl_add_u64 v[118:119], v[54:55], 0, v[114:115]
	v_lshl_add_u64 v[118:119], v[118:119], 0, vcc
	global_load_dwordx4 v[122:125], v[118:119], off
	global_load_dwordx4 v[126:129], v[118:119], off offset:1024
	s_mov_b32 vcc_lo, s17
	s_mov_b32 vcc_hi, 0
	s_lshl_b64 vcc, vcc, 11
	v_lshl_add_u64 v[120:121], v[58:59], 0, v[114:115]
	v_lshl_add_u64 v[120:121], v[120:121], 0, vcc
	s_mov_b64 vcc, 0x200000
	global_load_dwordx4 v[130:133], v[120:121], off nt
	global_load_dwordx4 v[134:137], v[120:121], off offset:1024 nt
	v_lshl_add_u64 v[120:121], v[120:121], 0, vcc
	global_load_dwordx4 v[138:141], v[120:121], off nt
	global_load_dwordx4 v[142:145], v[120:121], off offset:1024 nt
	v_lshl_add_u64 v[120:121], v[120:121], 0, vcc
	global_load_dwordx4 v[146:149], v[120:121], off nt
	global_load_dwordx4 v[150:153], v[120:121], off offset:1024 nt
	v_lshl_add_u64 v[120:121], v[120:121], 0, vcc
	global_load_dwordx4 v[154:157], v[120:121], off nt
	global_load_dwordx4 v[158:161], v[120:121], off offset:1024 nt
	v_mov_b32_e32 v220, 0x3a800000
	v_mov_b32_e32 v221, 0x358637bd
	s_waitcnt vmcnt(10)
	v_pk_add_f32 v[82:83], v[82:83], 1.0 op_sel_hi:[1,0]
	v_pk_add_f32 v[84:85], v[84:85], 1.0 op_sel_hi:[1,0]
	v_pk_add_f32 v[86:87], v[86:87], 1.0 op_sel_hi:[1,0]
	v_pk_add_f32 v[88:89], v[88:89], 1.0 op_sel_hi:[1,0]
	v_pk_add_f32 v[90:91], v[90:91], 1.0 op_sel_hi:[1,0]
	v_pk_add_f32 v[92:93], v[92:93], 1.0 op_sel_hi:[1,0]
	v_pk_add_f32 v[94:95], v[94:95], 1.0 op_sel_hi:[1,0]
	v_pk_add_f32 v[96:97], v[96:97], 1.0 op_sel_hi:[1,0]
	v_pk_mul_f32 v[66:67], v[66:67], v[82:83]
	v_pk_mul_f32 v[68:69], v[68:69], v[84:85]
	v_pk_mul_f32 v[70:71], v[70:71], v[86:87]
	v_pk_mul_f32 v[72:73], v[72:73], v[88:89]
	v_pk_mul_f32 v[74:75], v[74:75], v[90:91]
	v_pk_mul_f32 v[76:77], v[76:77], v[92:93]
	v_pk_mul_f32 v[78:79], v[78:79], v[94:95]
	v_pk_mul_f32 v[80:81], v[80:81], v[96:97]
	s_waitcnt vmcnt(8)
	v_lshlrev_b32_e32 v82, 16, v122
	v_and_b32_e32 v83, 0xffff0000, v122
	v_lshlrev_b32_e32 v84, 16, v123
	v_and_b32_e32 v85, 0xffff0000, v123
	v_lshlrev_b32_e32 v86, 16, v124
	v_and_b32_e32 v87, 0xffff0000, v124
	v_lshlrev_b32_e32 v88, 16, v125
	v_and_b32_e32 v89, 0xffff0000, v125
	v_lshlrev_b32_e32 v90, 16, v126
	v_and_b32_e32 v91, 0xffff0000, v126
	v_lshlrev_b32_e32 v92, 16, v127
	v_and_b32_e32 v93, 0xffff0000, v127
	v_lshlrev_b32_e32 v94, 16, v128
	v_and_b32_e32 v95, 0xffff0000, v128
	v_lshlrev_b32_e32 v96, 16, v129
	v_and_b32_e32 v97, 0xffff0000, v129
	s_waitcnt vmcnt(6)
	v_lshlrev_b32_e32 v218, 16, v130
	v_and_b32_e32 v219, 0xffff0000, v130
	v_pk_add_f32 v[82:83], v[82:83], v[218:219]
	v_lshlrev_b32_e32 v218, 16, v131
	v_and_b32_e32 v219, 0xffff0000, v131
	v_pk_add_f32 v[84:85], v[84:85], v[218:219]
	v_lshlrev_b32_e32 v218, 16, v132
	v_and_b32_e32 v219, 0xffff0000, v132
	v_pk_add_f32 v[86:87], v[86:87], v[218:219]
	v_lshlrev_b32_e32 v218, 16, v133
	v_and_b32_e32 v219, 0xffff0000, v133
	v_pk_add_f32 v[88:89], v[88:89], v[218:219]
	v_lshlrev_b32_e32 v218, 16, v134
	v_and_b32_e32 v219, 0xffff0000, v134
	v_pk_add_f32 v[90:91], v[90:91], v[218:219]
	v_lshlrev_b32_e32 v218, 16, v135
	v_and_b32_e32 v219, 0xffff0000, v135
	v_pk_add_f32 v[92:93], v[92:93], v[218:219]
	v_lshlrev_b32_e32 v218, 16, v136
	v_and_b32_e32 v219, 0xffff0000, v136
	v_pk_add_f32 v[94:95], v[94:95], v[218:219]
	v_lshlrev_b32_e32 v218, 16, v137
	v_and_b32_e32 v219, 0xffff0000, v137
	v_pk_add_f32 v[96:97], v[96:97], v[218:219]
	s_waitcnt vmcnt(4)
	v_lshlrev_b32_e32 v218, 16, v138
	v_and_b32_e32 v219, 0xffff0000, v138
	v_pk_add_f32 v[82:83], v[82:83], v[218:219]
	v_lshlrev_b32_e32 v218, 16, v139
	v_and_b32_e32 v219, 0xffff0000, v139
	v_pk_add_f32 v[84:85], v[84:85], v[218:219]
	v_lshlrev_b32_e32 v218, 16, v140
	v_and_b32_e32 v219, 0xffff0000, v140
	v_pk_add_f32 v[86:87], v[86:87], v[218:219]
	v_lshlrev_b32_e32 v218, 16, v141
	v_and_b32_e32 v219, 0xffff0000, v141
	v_pk_add_f32 v[88:89], v[88:89], v[218:219]
	v_lshlrev_b32_e32 v218, 16, v142
	v_and_b32_e32 v219, 0xffff0000, v142
	v_pk_add_f32 v[90:91], v[90:91], v[218:219]
	v_lshlrev_b32_e32 v218, 16, v143
	v_and_b32_e32 v219, 0xffff0000, v143
	v_pk_add_f32 v[92:93], v[92:93], v[218:219]
	v_lshlrev_b32_e32 v218, 16, v144
	v_and_b32_e32 v219, 0xffff0000, v144
	v_pk_add_f32 v[94:95], v[94:95], v[218:219]
	v_lshlrev_b32_e32 v218, 16, v145
	v_and_b32_e32 v219, 0xffff0000, v145
	v_pk_add_f32 v[96:97], v[96:97], v[218:219]
	s_waitcnt vmcnt(2)
	v_lshlrev_b32_e32 v218, 16, v146
	v_and_b32_e32 v219, 0xffff0000, v146
	v_pk_add_f32 v[82:83], v[82:83], v[218:219]
	v_lshlrev_b32_e32 v218, 16, v147
	v_and_b32_e32 v219, 0xffff0000, v147
	v_pk_add_f32 v[84:85], v[84:85], v[218:219]
	v_lshlrev_b32_e32 v218, 16, v148
	v_and_b32_e32 v219, 0xffff0000, v148
	v_pk_add_f32 v[86:87], v[86:87], v[218:219]
	v_lshlrev_b32_e32 v218, 16, v149
	v_and_b32_e32 v219, 0xffff0000, v149
	v_pk_add_f32 v[88:89], v[88:89], v[218:219]
	v_lshlrev_b32_e32 v218, 16, v150
	v_and_b32_e32 v219, 0xffff0000, v150
	v_pk_add_f32 v[90:91], v[90:91], v[218:219]
	v_lshlrev_b32_e32 v218, 16, v151
	v_and_b32_e32 v219, 0xffff0000, v151
	v_pk_add_f32 v[92:93], v[92:93], v[218:219]
	v_lshlrev_b32_e32 v218, 16, v152
	v_and_b32_e32 v219, 0xffff0000, v152
	v_pk_add_f32 v[94:95], v[94:95], v[218:219]
	v_lshlrev_b32_e32 v218, 16, v153
	v_and_b32_e32 v219, 0xffff0000, v153
	v_pk_add_f32 v[96:97], v[96:97], v[218:219]
	s_waitcnt vmcnt(0)
	v_lshlrev_b32_e32 v218, 16, v154
	v_and_b32_e32 v219, 0xffff0000, v154
	v_pk_add_f32 v[82:83], v[82:83], v[218:219]
	v_lshlrev_b32_e32 v218, 16, v155
	v_and_b32_e32 v219, 0xffff0000, v155
	v_pk_add_f32 v[84:85], v[84:85], v[218:219]
	v_lshlrev_b32_e32 v218, 16, v156
	v_and_b32_e32 v219, 0xffff0000, v156
	v_pk_add_f32 v[86:87], v[86:87], v[218:219]
	v_lshlrev_b32_e32 v218, 16, v157
	v_and_b32_e32 v219, 0xffff0000, v157
	v_pk_add_f32 v[88:89], v[88:89], v[218:219]
	v_lshlrev_b32_e32 v218, 16, v158
	v_and_b32_e32 v219, 0xffff0000, v158
	v_pk_add_f32 v[90:91], v[90:91], v[218:219]
	v_lshlrev_b32_e32 v218, 16, v159
	v_and_b32_e32 v219, 0xffff0000, v159
	v_pk_add_f32 v[92:93], v[92:93], v[218:219]
	v_lshlrev_b32_e32 v218, 16, v160
	v_and_b32_e32 v219, 0xffff0000, v160
	v_pk_add_f32 v[94:95], v[94:95], v[218:219]
	v_lshlrev_b32_e32 v218, 16, v161
	v_and_b32_e32 v219, 0xffff0000, v161
	v_pk_add_f32 v[96:97], v[96:97], v[218:219]
	v_cvt_pk_bf16_f32 v122, v82, v83
	v_cvt_pk_bf16_f32 v123, v84, v85
	v_cvt_pk_bf16_f32 v124, v86, v87
	v_cvt_pk_bf16_f32 v125, v88, v89
	v_cvt_pk_bf16_f32 v126, v90, v91
	v_cvt_pk_bf16_f32 v127, v92, v93
	v_cvt_pk_bf16_f32 v128, v94, v95
	v_cvt_pk_bf16_f32 v129, v96, v97
	global_store_dwordx4 v[118:119], v[122:125], off
	global_store_dwordx4 v[118:119], v[126:129], off offset:1024
	v_mul_f32_e32 v218, v82, v82
	v_mul_f32_e32 v219, v83, v83
	v_fmac_f32_e32 v218, v84, v84
	v_fmac_f32_e32 v219, v85, v85
	v_fmac_f32_e32 v218, v86, v86
	v_fmac_f32_e32 v219, v87, v87
	v_fmac_f32_e32 v218, v88, v88
	v_fmac_f32_e32 v219, v89, v89
	v_fmac_f32_e32 v218, v90, v90
	v_fmac_f32_e32 v219, v91, v91
	v_fmac_f32_e32 v218, v92, v92
	v_fmac_f32_e32 v219, v93, v93
	v_fmac_f32_e32 v218, v94, v94
	v_fmac_f32_e32 v219, v95, v95
	v_fmac_f32_e32 v218, v96, v96
	v_fmac_f32_e32 v219, v97, v97
	v_add_f32_e32 v218, v218, v219
	s_nop 1
	v_add_f32_dpp v218, v218, v218 quad_perm:[1,0,3,2] row_mask:0xf bank_mask:0xf
	s_nop 1
	v_add_f32_dpp v218, v218, v218 quad_perm:[2,3,0,1] row_mask:0xf bank_mask:0xf
	s_nop 1
	v_add_f32_dpp v218, v218, v218 row_half_mirror row_mask:0xf bank_mask:0xf
	s_nop 1
	v_add_f32_dpp v218, v218, v218 row_mirror row_mask:0xf bank_mask:0xf
	s_nop 1
	v_add_f32_dpp v218, v218, v218 row_bcast:15 row_mask:0xa bank_mask:0xf
	s_nop 1
	v_add_f32_dpp v218, v218, v218 row_bcast:31 row_mask:0xc bank_mask:0xf
	s_nop 1
	v_readlane_b32 vcc_lo, v218, 63
	s_nop 2
	v_fma_f32 v222, vcc_lo, v220, v221
	v_rsq_f32_e32 v222, v222
	s_mov_b64 vcc, 0x4400000
	v_lshl_add_u64 v[118:119], v[118:119], 0, vcc
	v_pk_mul_f32 v[82:83], v[82:83], v[222:223] op_sel_hi:[1,0]
	v_pk_fma_f32 v[82:83], v[82:83], v[66:67], v[98:99]
	v_pk_mul_f32 v[84:85], v[84:85], v[222:223] op_sel_hi:[1,0]
	v_pk_fma_f32 v[84:85], v[84:85], v[68:69], v[100:101]
	v_pk_mul_f32 v[86:87], v[86:87], v[222:223] op_sel_hi:[1,0]
	v_pk_fma_f32 v[86:87], v[86:87], v[70:71], v[102:103]
	v_pk_mul_f32 v[88:89], v[88:89], v[222:223] op_sel_hi:[1,0]
	v_pk_fma_f32 v[88:89], v[88:89], v[72:73], v[104:105]
	v_pk_mul_f32 v[90:91], v[90:91], v[222:223] op_sel_hi:[1,0]
	v_pk_fma_f32 v[90:91], v[90:91], v[74:75], v[106:107]
	v_pk_mul_f32 v[92:93], v[92:93], v[222:223] op_sel_hi:[1,0]
	v_pk_fma_f32 v[92:93], v[92:93], v[76:77], v[108:109]
	v_pk_mul_f32 v[94:95], v[94:95], v[222:223] op_sel_hi:[1,0]
	v_pk_fma_f32 v[94:95], v[94:95], v[78:79], v[110:111]
	v_pk_mul_f32 v[96:97], v[96:97], v[222:223] op_sel_hi:[1,0]
	v_pk_fma_f32 v[96:97], v[96:97], v[80:81], v[112:113]
	v_cvt_pk_bf16_f32 v66, v82, v83
	v_cvt_pk_bf16_f32 v67, v84, v85
	v_cvt_pk_bf16_f32 v68, v86, v87
	v_cvt_pk_bf16_f32 v69, v88, v89
	v_cvt_pk_bf16_f32 v70, v90, v91
	v_cvt_pk_bf16_f32 v71, v92, v93
	v_cvt_pk_bf16_f32 v72, v94, v95
	v_cvt_pk_bf16_f32 v73, v96, v97
	global_store_dwordx4 v[118:119], v[66:69], off
	global_store_dwordx4 v[118:119], v[70:73], off offset:1024
	s_branch .Lnc_done
.Lnc_11:
	s_mov_b64 vcc, 0x24000
	v_lshl_add_u64 v[118:119], v[62:63], 0, v[116:117]
	v_lshl_add_u64 v[120:121], v[60:61], 0, v[116:117]
	v_lshl_add_u64 v[118:119], v[118:119], 0, vcc
	v_lshl_add_u64 v[120:121], v[120:121], 0, vcc
	v_lshl_add_u64 v[218:219], v[52:53], 0, v[116:117]
	global_load_dwordx4 v[66:69], v[218:219], off
	global_load_dwordx4 v[70:73], v[218:219], off offset:16
	global_load_dwordx4 v[74:77], v[218:219], off offset:2048
	global_load_dwordx4 v[78:81], v[218:219], off offset:2064
	global_load_dwordx4 v[82:85], v[118:119], off
	global_load_dwordx4 v[86:89], v[118:119], off offset:16
	global_load_dwordx4 v[90:93], v[118:119], off offset:2048
	global_load_dwordx4 v[94:97], v[118:119], off offset:2064
	global_load_dwordx4 v[98:101], v[120:121], off
	global_load_dwordx4 v[102:105], v[120:121], off offset:16
	global_load_dwordx4 v[106:109], v[120:121], off offset:2048
	global_load_dwordx4 v[110:113], v[120:121], off offset:2064
	s_mov_b32 vcc_lo, s25
	s_mov_b32 vcc_hi, 0
	s_lshl_b64 vcc, vcc, 11
	v_lshl_add_u64 v[118:119], v[54:55], 0, v[114:115]
	v_lshl_add_u64 v[118:119], v[118:119], 0, vcc
	global_load_dwordx4 v[122:125], v[118:119], off
	global_load_dwordx4 v[126:129], v[118:119], off offset:1024
	s_mov_b32 vcc_lo, s17
	s_mov_b32 vcc_hi, 0
	s_lshl_b64 vcc, vcc, 11
	v_lshl_add_u64 v[120:121], v[58:59], 0, v[114:115]
	v_lshl_add_u64 v[120:121], v[120:121], 0, vcc
	s_mov_b64 vcc, 0x200000
	global_load_dwordx4 v[130:133], v[120:121], off nt
	global_load_dwordx4 v[134:137], v[120:121], off offset:1024 nt
	v_lshl_add_u64 v[120:121], v[120:121], 0, vcc
	global_load_dwordx4 v[138:141], v[120:121], off nt
	global_load_dwordx4 v[142:145], v[120:121], off offset:1024 nt
	v_lshl_add_u64 v[120:121], v[120:121], 0, vcc
	global_load_dwordx4 v[146:149], v[120:121], off nt
	global_load_dwordx4 v[150:153], v[120:121], off offset:1024 nt
	v_lshl_add_u64 v[120:121], v[120:121], 0, vcc
	global_load_dwordx4 v[154:157], v[120:121], off nt
	global_load_dwordx4 v[158:161], v[120:121], off offset:1024 nt
	v_lshl_add_u64 v[120:121], v[120:121], 0, vcc
	global_load_dwordx4 v[162:165], v[120:121], off nt
	global_load_dwordx4 v[166:169], v[120:121], off offset:1024 nt
	v_lshl_add_u64 v[120:121], v[120:121], 0, vcc
	global_load_dwordx4 v[170:173], v[120:121], off nt
	global_load_dwordx4 v[174:177], v[120:121], off offset:1024 nt
	v_lshl_add_u64 v[120:121], v[120:121], 0, vcc
	global_load_dwordx4 v[178:181], v[120:121], off nt
	global_load_dwordx4 v[182:185], v[120:121], off offset:1024 nt
	v_lshl_add_u64 v[120:121], v[120:121], 0, vcc
	global_load_dwordx4 v[186:189], v[120:121], off nt
	global_load_dwordx4 v[190:193], v[120:121], off offset:1024 nt
	v_lshl_add_u64 v[120:121], v[120:121], 0, vcc
	global_load_dwordx4 v[194:197], v[120:121], off nt
	global_load_dwordx4 v[198:201], v[120:121], off offset:1024 nt
	v_lshl_add_u64 v[120:121], v[120:121], 0, vcc
	global_load_dwordx4 v[202:205], v[120:121], off nt
	global_load_dwordx4 v[206:209], v[120:121], off offset:1024 nt
	v_lshl_add_u64 v[120:121], v[120:121], 0, vcc
	global_load_dwordx4 v[210:213], v[120:121], off nt
	global_load_dwordx4 v[214:217], v[120:121], off offset:1024 nt
	v_mov_b32_e32 v220, 0x3a800000
	v_mov_b32_e32 v221, 0x358637bd
	s_waitcnt vmcnt(24)
	v_pk_add_f32 v[82:83], v[82:83], 1.0 op_sel_hi:[1,0]
	v_pk_add_f32 v[84:85], v[84:85], 1.0 op_sel_hi:[1,0]
	v_pk_add_f32 v[86:87], v[86:87], 1.0 op_sel_hi:[1,0]
	v_pk_add_f32 v[88:89], v[88:89], 1.0 op_sel_hi:[1,0]
	v_pk_add_f32 v[90:91], v[90:91], 1.0 op_sel_hi:[1,0]
	v_pk_add_f32 v[92:93], v[92:93], 1.0 op_sel_hi:[1,0]
	v_pk_add_f32 v[94:95], v[94:95], 1.0 op_sel_hi:[1,0]
	v_pk_add_f32 v[96:97], v[96:97], 1.0 op_sel_hi:[1,0]
	v_pk_mul_f32 v[66:67], v[66:67], v[82:83]
	v_pk_mul_f32 v[68:69], v[68:69], v[84:85]
	v_pk_mul_f32 v[70:71], v[70:71], v[86:87]
	v_pk_mul_f32 v[72:73], v[72:73], v[88:89]
	v_pk_mul_f32 v[74:75], v[74:75], v[90:91]
	v_pk_mul_f32 v[76:77], v[76:77], v[92:93]
	v_pk_mul_f32 v[78:79], v[78:79], v[94:95]
	v_pk_mul_f32 v[80:81], v[80:81], v[96:97]
	s_waitcnt vmcnt(22)
	v_lshlrev_b32_e32 v82, 16, v122
	v_and_b32_e32 v83, 0xffff0000, v122
	v_lshlrev_b32_e32 v84, 16, v123
	v_and_b32_e32 v85, 0xffff0000, v123
	v_lshlrev_b32_e32 v86, 16, v124
	v_and_b32_e32 v87, 0xffff0000, v124
	v_lshlrev_b32_e32 v88, 16, v125
	v_and_b32_e32 v89, 0xffff0000, v125
	v_lshlrev_b32_e32 v90, 16, v126
	v_and_b32_e32 v91, 0xffff0000, v126
	v_lshlrev_b32_e32 v92, 16, v127
	v_and_b32_e32 v93, 0xffff0000, v127
	v_lshlrev_b32_e32 v94, 16, v128
	v_and_b32_e32 v95, 0xffff0000, v128
	v_lshlrev_b32_e32 v96, 16, v129
	v_and_b32_e32 v97, 0xffff0000, v129
	s_waitcnt vmcnt(20)
	v_lshlrev_b32_e32 v218, 16, v130
	v_and_b32_e32 v219, 0xffff0000, v130
	v_pk_add_f32 v[82:83], v[82:83], v[218:219]
	v_lshlrev_b32_e32 v218, 16, v131
	v_and_b32_e32 v219, 0xffff0000, v131
	v_pk_add_f32 v[84:85], v[84:85], v[218:219]
	v_lshlrev_b32_e32 v218, 16, v132
	v_and_b32_e32 v219, 0xffff0000, v132
	v_pk_add_f32 v[86:87], v[86:87], v[218:219]
	v_lshlrev_b32_e32 v218, 16, v133
	v_and_b32_e32 v219, 0xffff0000, v133
	v_pk_add_f32 v[88:89], v[88:89], v[218:219]
	v_lshlrev_b32_e32 v218, 16, v134
	v_and_b32_e32 v219, 0xffff0000, v134
	v_pk_add_f32 v[90:91], v[90:91], v[218:219]
	v_lshlrev_b32_e32 v218, 16, v135
	v_and_b32_e32 v219, 0xffff0000, v135
	v_pk_add_f32 v[92:93], v[92:93], v[218:219]
	v_lshlrev_b32_e32 v218, 16, v136
	v_and_b32_e32 v219, 0xffff0000, v136
	v_pk_add_f32 v[94:95], v[94:95], v[218:219]
	v_lshlrev_b32_e32 v218, 16, v137
	v_and_b32_e32 v219, 0xffff0000, v137
	v_pk_add_f32 v[96:97], v[96:97], v[218:219]
	s_waitcnt vmcnt(18)
	v_lshlrev_b32_e32 v218, 16, v138
	v_and_b32_e32 v219, 0xffff0000, v138
	v_pk_add_f32 v[82:83], v[82:83], v[218:219]
	v_lshlrev_b32_e32 v218, 16, v139
	v_and_b32_e32 v219, 0xffff0000, v139
	v_pk_add_f32 v[84:85], v[84:85], v[218:219]
	v_lshlrev_b32_e32 v218, 16, v140
	v_and_b32_e32 v219, 0xffff0000, v140
	v_pk_add_f32 v[86:87], v[86:87], v[218:219]
	v_lshlrev_b32_e32 v218, 16, v141
	v_and_b32_e32 v219, 0xffff0000, v141
	v_pk_add_f32 v[88:89], v[88:89], v[218:219]
	v_lshlrev_b32_e32 v218, 16, v142
	v_and_b32_e32 v219, 0xffff0000, v142
	v_pk_add_f32 v[90:91], v[90:91], v[218:219]
	v_lshlrev_b32_e32 v218, 16, v143
	v_and_b32_e32 v219, 0xffff0000, v143
	v_pk_add_f32 v[92:93], v[92:93], v[218:219]
	v_lshlrev_b32_e32 v218, 16, v144
	v_and_b32_e32 v219, 0xffff0000, v144
	v_pk_add_f32 v[94:95], v[94:95], v[218:219]
	v_lshlrev_b32_e32 v218, 16, v145
	v_and_b32_e32 v219, 0xffff0000, v145
	v_pk_add_f32 v[96:97], v[96:97], v[218:219]
	s_waitcnt vmcnt(16)
	v_lshlrev_b32_e32 v218, 16, v146
	v_and_b32_e32 v219, 0xffff0000, v146
	v_pk_add_f32 v[82:83], v[82:83], v[218:219]
	v_lshlrev_b32_e32 v218, 16, v147
	v_and_b32_e32 v219, 0xffff0000, v147
	v_pk_add_f32 v[84:85], v[84:85], v[218:219]
	v_lshlrev_b32_e32 v218, 16, v148
	v_and_b32_e32 v219, 0xffff0000, v148
	v_pk_add_f32 v[86:87], v[86:87], v[218:219]
	v_lshlrev_b32_e32 v218, 16, v149
	v_and_b32_e32 v219, 0xffff0000, v149
	v_pk_add_f32 v[88:89], v[88:89], v[218:219]
	v_lshlrev_b32_e32 v218, 16, v150
	v_and_b32_e32 v219, 0xffff0000, v150
	v_pk_add_f32 v[90:91], v[90:91], v[218:219]
	v_lshlrev_b32_e32 v218, 16, v151
	v_and_b32_e32 v219, 0xffff0000, v151
	v_pk_add_f32 v[92:93], v[92:93], v[218:219]
	v_lshlrev_b32_e32 v218, 16, v152
	v_and_b32_e32 v219, 0xffff0000, v152
	v_pk_add_f32 v[94:95], v[94:95], v[218:219]
	v_lshlrev_b32_e32 v218, 16, v153
	v_and_b32_e32 v219, 0xffff0000, v153
	v_pk_add_f32 v[96:97], v[96:97], v[218:219]
	s_waitcnt vmcnt(14)
	v_lshlrev_b32_e32 v218, 16, v154
	v_and_b32_e32 v219, 0xffff0000, v154
	v_pk_add_f32 v[82:83], v[82:83], v[218:219]
	v_lshlrev_b32_e32 v218, 16, v155
	v_and_b32_e32 v219, 0xffff0000, v155
	v_pk_add_f32 v[84:85], v[84:85], v[218:219]
	v_lshlrev_b32_e32 v218, 16, v156
	v_and_b32_e32 v219, 0xffff0000, v156
	v_pk_add_f32 v[86:87], v[86:87], v[218:219]
	v_lshlrev_b32_e32 v218, 16, v157
	v_and_b32_e32 v219, 0xffff0000, v157
	v_pk_add_f32 v[88:89], v[88:89], v[218:219]
	v_lshlrev_b32_e32 v218, 16, v158
	v_and_b32_e32 v219, 0xffff0000, v158
	v_pk_add_f32 v[90:91], v[90:91], v[218:219]
	v_lshlrev_b32_e32 v218, 16, v159
	v_and_b32_e32 v219, 0xffff0000, v159
	v_pk_add_f32 v[92:93], v[92:93], v[218:219]
	v_lshlrev_b32_e32 v218, 16, v160
	v_and_b32_e32 v219, 0xffff0000, v160
	v_pk_add_f32 v[94:95], v[94:95], v[218:219]
	v_lshlrev_b32_e32 v218, 16, v161
	v_and_b32_e32 v219, 0xffff0000, v161
	v_pk_add_f32 v[96:97], v[96:97], v[218:219]
	s_waitcnt vmcnt(12)
	v_lshlrev_b32_e32 v218, 16, v162
	v_and_b32_e32 v219, 0xffff0000, v162
	v_pk_add_f32 v[82:83], v[82:83], v[218:219]
	v_lshlrev_b32_e32 v218, 16, v163
	v_and_b32_e32 v219, 0xffff0000, v163
	v_pk_add_f32 v[84:85], v[84:85], v[218:219]
	v_lshlrev_b32_e32 v218, 16, v164
	v_and_b32_e32 v219, 0xffff0000, v164
	v_pk_add_f32 v[86:87], v[86:87], v[218:219]
	v_lshlrev_b32_e32 v218, 16, v165
	v_and_b32_e32 v219, 0xffff0000, v165
	v_pk_add_f32 v[88:89], v[88:89], v[218:219]
	v_lshlrev_b32_e32 v218, 16, v166
	v_and_b32_e32 v219, 0xffff0000, v166
	v_pk_add_f32 v[90:91], v[90:91], v[218:219]
	v_lshlrev_b32_e32 v218, 16, v167
	v_and_b32_e32 v219, 0xffff0000, v167
	v_pk_add_f32 v[92:93], v[92:93], v[218:219]
	v_lshlrev_b32_e32 v218, 16, v168
	v_and_b32_e32 v219, 0xffff0000, v168
	v_pk_add_f32 v[94:95], v[94:95], v[218:219]
	v_lshlrev_b32_e32 v218, 16, v169
	v_and_b32_e32 v219, 0xffff0000, v169
	v_pk_add_f32 v[96:97], v[96:97], v[218:219]
	s_waitcnt vmcnt(10)
	v_lshlrev_b32_e32 v218, 16, v170
	v_and_b32_e32 v219, 0xffff0000, v170
	v_pk_add_f32 v[82:83], v[82:83], v[218:219]
	v_lshlrev_b32_e32 v218, 16, v171
	v_and_b32_e32 v219, 0xffff0000, v171
	v_pk_add_f32 v[84:85], v[84:85], v[218:219]
	v_lshlrev_b32_e32 v218, 16, v172
	v_and_b32_e32 v219, 0xffff0000, v172
	v_pk_add_f32 v[86:87], v[86:87], v[218:219]
	v_lshlrev_b32_e32 v218, 16, v173
	v_and_b32_e32 v219, 0xffff0000, v173
	v_pk_add_f32 v[88:89], v[88:89], v[218:219]
	v_lshlrev_b32_e32 v218, 16, v174
	v_and_b32_e32 v219, 0xffff0000, v174
	v_pk_add_f32 v[90:91], v[90:91], v[218:219]
	v_lshlrev_b32_e32 v218, 16, v175
	v_and_b32_e32 v219, 0xffff0000, v175
	v_pk_add_f32 v[92:93], v[92:93], v[218:219]
	v_lshlrev_b32_e32 v218, 16, v176
	v_and_b32_e32 v219, 0xffff0000, v176
	v_pk_add_f32 v[94:95], v[94:95], v[218:219]
	v_lshlrev_b32_e32 v218, 16, v177
	v_and_b32_e32 v219, 0xffff0000, v177
	v_pk_add_f32 v[96:97], v[96:97], v[218:219]
	s_waitcnt vmcnt(8)
	v_lshlrev_b32_e32 v218, 16, v178
	v_and_b32_e32 v219, 0xffff0000, v178
	v_pk_add_f32 v[82:83], v[82:83], v[218:219]
	v_lshlrev_b32_e32 v218, 16, v179
	v_and_b32_e32 v219, 0xffff0000, v179
	v_pk_add_f32 v[84:85], v[84:85], v[218:219]
	v_lshlrev_b32_e32 v218, 16, v180
	v_and_b32_e32 v219, 0xffff0000, v180
	v_pk_add_f32 v[86:87], v[86:87], v[218:219]
	v_lshlrev_b32_e32 v218, 16, v181
	v_and_b32_e32 v219, 0xffff0000, v181
	v_pk_add_f32 v[88:89], v[88:89], v[218:219]
	v_lshlrev_b32_e32 v218, 16, v182
	v_and_b32_e32 v219, 0xffff0000, v182
	v_pk_add_f32 v[90:91], v[90:91], v[218:219]
	v_lshlrev_b32_e32 v218, 16, v183
	v_and_b32_e32 v219, 0xffff0000, v183
	v_pk_add_f32 v[92:93], v[92:93], v[218:219]
	v_lshlrev_b32_e32 v218, 16, v184
	v_and_b32_e32 v219, 0xffff0000, v184
	v_pk_add_f32 v[94:95], v[94:95], v[218:219]
	v_lshlrev_b32_e32 v218, 16, v185
	v_and_b32_e32 v219, 0xffff0000, v185
	v_pk_add_f32 v[96:97], v[96:97], v[218:219]
	s_waitcnt vmcnt(6)
	v_lshlrev_b32_e32 v218, 16, v186
	v_and_b32_e32 v219, 0xffff0000, v186
	v_pk_add_f32 v[82:83], v[82:83], v[218:219]
	v_lshlrev_b32_e32 v218, 16, v187
	v_and_b32_e32 v219, 0xffff0000, v187
	v_pk_add_f32 v[84:85], v[84:85], v[218:219]
	v_lshlrev_b32_e32 v218, 16, v188
	v_and_b32_e32 v219, 0xffff0000, v188
	v_pk_add_f32 v[86:87], v[86:87], v[218:219]
	v_lshlrev_b32_e32 v218, 16, v189
	v_and_b32_e32 v219, 0xffff0000, v189
	v_pk_add_f32 v[88:89], v[88:89], v[218:219]
	v_lshlrev_b32_e32 v218, 16, v190
	v_and_b32_e32 v219, 0xffff0000, v190
	v_pk_add_f32 v[90:91], v[90:91], v[218:219]
	v_lshlrev_b32_e32 v218, 16, v191
	v_and_b32_e32 v219, 0xffff0000, v191
	v_pk_add_f32 v[92:93], v[92:93], v[218:219]
	v_lshlrev_b32_e32 v218, 16, v192
	v_and_b32_e32 v219, 0xffff0000, v192
	v_pk_add_f32 v[94:95], v[94:95], v[218:219]
	v_lshlrev_b32_e32 v218, 16, v193
	v_and_b32_e32 v219, 0xffff0000, v193
	v_pk_add_f32 v[96:97], v[96:97], v[218:219]
	s_waitcnt vmcnt(4)
	v_lshlrev_b32_e32 v218, 16, v194
	v_and_b32_e32 v219, 0xffff0000, v194
	v_pk_add_f32 v[82:83], v[82:83], v[218:219]
	v_lshlrev_b32_e32 v218, 16, v195
	v_and_b32_e32 v219, 0xffff0000, v195
	v_pk_add_f32 v[84:85], v[84:85], v[218:219]
	v_lshlrev_b32_e32 v218, 16, v196
	v_and_b32_e32 v219, 0xffff0000, v196
	v_pk_add_f32 v[86:87], v[86:87], v[218:219]
	v_lshlrev_b32_e32 v218, 16, v197
	v_and_b32_e32 v219, 0xffff0000, v197
	v_pk_add_f32 v[88:89], v[88:89], v[218:219]
	v_lshlrev_b32_e32 v218, 16, v198
	v_and_b32_e32 v219, 0xffff0000, v198
	v_pk_add_f32 v[90:91], v[90:91], v[218:219]
	v_lshlrev_b32_e32 v218, 16, v199
	v_and_b32_e32 v219, 0xffff0000, v199
	v_pk_add_f32 v[92:93], v[92:93], v[218:219]
	v_lshlrev_b32_e32 v218, 16, v200
	v_and_b32_e32 v219, 0xffff0000, v200
	v_pk_add_f32 v[94:95], v[94:95], v[218:219]
	v_lshlrev_b32_e32 v218, 16, v201
	v_and_b32_e32 v219, 0xffff0000, v201
	v_pk_add_f32 v[96:97], v[96:97], v[218:219]
	s_waitcnt vmcnt(2)
	v_lshlrev_b32_e32 v218, 16, v202
	v_and_b32_e32 v219, 0xffff0000, v202
	v_pk_add_f32 v[82:83], v[82:83], v[218:219]
	v_lshlrev_b32_e32 v218, 16, v203
	v_and_b32_e32 v219, 0xffff0000, v203
	v_pk_add_f32 v[84:85], v[84:85], v[218:219]
	v_lshlrev_b32_e32 v218, 16, v204
	v_and_b32_e32 v219, 0xffff0000, v204
	v_pk_add_f32 v[86:87], v[86:87], v[218:219]
	v_lshlrev_b32_e32 v218, 16, v205
	v_and_b32_e32 v219, 0xffff0000, v205
	v_pk_add_f32 v[88:89], v[88:89], v[218:219]
	v_lshlrev_b32_e32 v218, 16, v206
	v_and_b32_e32 v219, 0xffff0000, v206
	v_pk_add_f32 v[90:91], v[90:91], v[218:219]
	v_lshlrev_b32_e32 v218, 16, v207
	v_and_b32_e32 v219, 0xffff0000, v207
	v_pk_add_f32 v[92:93], v[92:93], v[218:219]
	v_lshlrev_b32_e32 v218, 16, v208
	v_and_b32_e32 v219, 0xffff0000, v208
	v_pk_add_f32 v[94:95], v[94:95], v[218:219]
	v_lshlrev_b32_e32 v218, 16, v209
	v_and_b32_e32 v219, 0xffff0000, v209
	v_pk_add_f32 v[96:97], v[96:97], v[218:219]
	s_waitcnt vmcnt(0)
	v_lshlrev_b32_e32 v218, 16, v210
	v_and_b32_e32 v219, 0xffff0000, v210
	v_pk_add_f32 v[82:83], v[82:83], v[218:219]
	v_lshlrev_b32_e32 v218, 16, v211
	v_and_b32_e32 v219, 0xffff0000, v211
	v_pk_add_f32 v[84:85], v[84:85], v[218:219]
	v_lshlrev_b32_e32 v218, 16, v212
	v_and_b32_e32 v219, 0xffff0000, v212
	v_pk_add_f32 v[86:87], v[86:87], v[218:219]
	v_lshlrev_b32_e32 v218, 16, v213
	v_and_b32_e32 v219, 0xffff0000, v213
	v_pk_add_f32 v[88:89], v[88:89], v[218:219]
	v_lshlrev_b32_e32 v218, 16, v214
	v_and_b32_e32 v219, 0xffff0000, v214
	v_pk_add_f32 v[90:91], v[90:91], v[218:219]
	v_lshlrev_b32_e32 v218, 16, v215
	v_and_b32_e32 v219, 0xffff0000, v215
	v_pk_add_f32 v[92:93], v[92:93], v[218:219]
	v_lshlrev_b32_e32 v218, 16, v216
	v_and_b32_e32 v219, 0xffff0000, v216
	v_pk_add_f32 v[94:95], v[94:95], v[218:219]
	v_lshlrev_b32_e32 v218, 16, v217
	v_and_b32_e32 v219, 0xffff0000, v217
	v_pk_add_f32 v[96:97], v[96:97], v[218:219]
	v_cvt_pk_bf16_f32 v122, v82, v83
	v_cvt_pk_bf16_f32 v123, v84, v85
	v_cvt_pk_bf16_f32 v124, v86, v87
	v_cvt_pk_bf16_f32 v125, v88, v89
	v_cvt_pk_bf16_f32 v126, v90, v91
	v_cvt_pk_bf16_f32 v127, v92, v93
	v_cvt_pk_bf16_f32 v128, v94, v95
	v_cvt_pk_bf16_f32 v129, v96, v97
	global_store_dwordx4 v[118:119], v[122:125], off
	global_store_dwordx4 v[118:119], v[126:129], off offset:1024
	v_mul_f32_e32 v218, v82, v82
	v_mul_f32_e32 v219, v83, v83
	v_fmac_f32_e32 v218, v84, v84
	v_fmac_f32_e32 v219, v85, v85
	v_fmac_f32_e32 v218, v86, v86
	v_fmac_f32_e32 v219, v87, v87
	v_fmac_f32_e32 v218, v88, v88
	v_fmac_f32_e32 v219, v89, v89
	v_fmac_f32_e32 v218, v90, v90
	v_fmac_f32_e32 v219, v91, v91
	v_fmac_f32_e32 v218, v92, v92
	v_fmac_f32_e32 v219, v93, v93
	v_fmac_f32_e32 v218, v94, v94
	v_fmac_f32_e32 v219, v95, v95
	v_fmac_f32_e32 v218, v96, v96
	v_fmac_f32_e32 v219, v97, v97
	v_add_f32_e32 v218, v218, v219
	s_nop 1
	v_add_f32_dpp v218, v218, v218 quad_perm:[1,0,3,2] row_mask:0xf bank_mask:0xf
	s_nop 1
	v_add_f32_dpp v218, v218, v218 quad_perm:[2,3,0,1] row_mask:0xf bank_mask:0xf
	s_nop 1
	v_add_f32_dpp v218, v218, v218 row_half_mirror row_mask:0xf bank_mask:0xf
	s_nop 1
	v_add_f32_dpp v218, v218, v218 row_mirror row_mask:0xf bank_mask:0xf
	s_nop 1
	v_add_f32_dpp v218, v218, v218 row_bcast:15 row_mask:0xa bank_mask:0xf
	s_nop 1
	v_add_f32_dpp v218, v218, v218 row_bcast:31 row_mask:0xc bank_mask:0xf
	s_nop 1
	v_readlane_b32 vcc_lo, v218, 63
	s_nop 2
	v_fma_f32 v222, vcc_lo, v220, v221
	v_rsq_f32_e32 v222, v222
	s_mov_b64 vcc, 0x4400000
	v_lshl_add_u64 v[118:119], v[118:119], 0, vcc
	v_pk_mul_f32 v[82:83], v[82:83], v[222:223] op_sel_hi:[1,0]
	v_pk_fma_f32 v[82:83], v[82:83], v[66:67], v[98:99]
	v_pk_mul_f32 v[84:85], v[84:85], v[222:223] op_sel_hi:[1,0]
	v_pk_fma_f32 v[84:85], v[84:85], v[68:69], v[100:101]
	v_pk_mul_f32 v[86:87], v[86:87], v[222:223] op_sel_hi:[1,0]
	v_pk_fma_f32 v[86:87], v[86:87], v[70:71], v[102:103]
	v_pk_mul_f32 v[88:89], v[88:89], v[222:223] op_sel_hi:[1,0]
	v_pk_fma_f32 v[88:89], v[88:89], v[72:73], v[104:105]
	v_pk_mul_f32 v[90:91], v[90:91], v[222:223] op_sel_hi:[1,0]
	v_pk_fma_f32 v[90:91], v[90:91], v[74:75], v[106:107]
	v_pk_mul_f32 v[92:93], v[92:93], v[222:223] op_sel_hi:[1,0]
	v_pk_fma_f32 v[92:93], v[92:93], v[76:77], v[108:109]
	v_pk_mul_f32 v[94:95], v[94:95], v[222:223] op_sel_hi:[1,0]
	v_pk_fma_f32 v[94:95], v[94:95], v[78:79], v[110:111]
	v_pk_mul_f32 v[96:97], v[96:97], v[222:223] op_sel_hi:[1,0]
	v_pk_fma_f32 v[96:97], v[96:97], v[80:81], v[112:113]
	v_cvt_pk_bf16_f32 v66, v82, v83
	v_cvt_pk_bf16_f32 v67, v84, v85
	v_cvt_pk_bf16_f32 v68, v86, v87
	v_cvt_pk_bf16_f32 v69, v88, v89
	v_cvt_pk_bf16_f32 v70, v90, v91
	v_cvt_pk_bf16_f32 v71, v92, v93
	v_cvt_pk_bf16_f32 v72, v94, v95
	v_cvt_pk_bf16_f32 v73, v96, v97
	global_store_dwordx4 v[118:119], v[66:69], off
	global_store_dwordx4 v[118:119], v[70:73], off offset:1024
	s_branch .Lnc_done
.Lnc_done:
	s_mov_b64 s[6:7], 0
.Lnc_skip:
	s_branch .LBB0_588
